# grid barrier: non-leaders poll the global release word directly (one hop fewer); plus x loads nt
# speedup vs baseline: 1.0293x; 1.0293x over previous
.LBB0_57:
	s_or_b64 exec, exec, s[28:29]
	v_cvt_f32_u32_e32 v4, v2
	s_waitcnt vmcnt(0)
	v_readfirstlane_b32 s16, v3
	v_sub_u32_e32 v3, 0, v2
	v_rcp_iflag_f32_e32 v4, v4
	v_add_u32_e32 v5, s16, v1
	v_mul_f32_e32 v4, 0x4f7ffffe, v4
	v_cvt_u32_f32_e32 v4, v4
	v_mul_lo_u32 v1, v3, v4
	v_mul_hi_u32 v1, v4, v1
	v_add_u32_e32 v1, v4, v1
	v_mul_hi_u32 v1, v5, v1
	v_mul_lo_u32 v3, v1, v2
	v_sub_u32_e32 v3, v5, v3
	v_add_u32_e32 v4, 1, v1
	v_cmp_ge_u32_e32 vcc, v3, v2
	s_nop 1
	v_cndmask_b32_e32 v1, v1, v4, vcc
	v_sub_u32_e32 v4, v3, v2
	v_cndmask_b32_e32 v3, v3, v4, vcc
	v_add_u32_e32 v4, 1, v1
	v_cmp_ge_u32_e32 vcc, v3, v2
	v_add_u32_e32 v3, 1, v5
	s_nop 0
	v_cndmask_b32_e32 v1, v1, v4, vcc
	v_mul_lo_u32 v4, v2, v1
	v_add_u32_e32 v2, v4, v2
	v_cmp_ne_u32_e32 vcc, v3, v2
	s_and_saveexec_b64 s[16:17], vcc
	s_xor_b64 s[16:17], exec, s[16:17]
	s_cbranch_execz .LBB0_71
	s_waitcnt lgkmcnt(0)
	v_mov_b32_e32 v0, 0x3100
	global_load_dword v0, v0, s[54:55] offset:1024 sc1
	s_add_u32 s48, s54, 0x3500
	s_addc_u32 s49, s55, 0
	s_waitcnt vmcnt(0)
	v_cmp_eq_u32_e32 vcc, v0, v1
	s_and_saveexec_b64 s[28:29], vcc
	s_cbranch_execz .LBB0_70
	s_add_u32 s46, s52, 0x1200
	s_addc_u32 s47, s53, 0
	s_mov_b32 s64, 1
	s_mov_b64 s[50:51], 0
	v_mov_b32_e32 v0, 0
	s_branch .LBB0_61

.LBB0_209:
	s_or_b64 exec, exec, s[16:17]
	v_cvt_f32_u32_e32 v4, v2
	s_waitcnt vmcnt(0)
	v_readfirstlane_b32 s6, v3
	v_sub_u32_e32 v3, 0, v2
	v_rcp_iflag_f32_e32 v4, v4
	v_add_u32_e32 v5, s6, v1
	v_mul_f32_e32 v4, 0x4f7ffffe, v4
	v_cvt_u32_f32_e32 v4, v4
	v_mul_lo_u32 v1, v3, v4
	v_mul_hi_u32 v1, v4, v1
	v_add_u32_e32 v1, v4, v1
	v_mul_hi_u32 v1, v5, v1
	v_mul_lo_u32 v3, v1, v2
	v_sub_u32_e32 v3, v5, v3
	v_add_u32_e32 v4, 1, v1
	v_cmp_ge_u32_e32 vcc, v3, v2
	s_nop 1
	v_cndmask_b32_e32 v1, v1, v4, vcc
	v_sub_u32_e32 v4, v3, v2
	v_cndmask_b32_e32 v3, v3, v4, vcc
	v_add_u32_e32 v4, 1, v1
	v_cmp_ge_u32_e32 vcc, v3, v2
	v_add_u32_e32 v3, 1, v5
	s_nop 0
	v_cndmask_b32_e32 v1, v1, v4, vcc
	v_mul_lo_u32 v4, v2, v1
	v_add_u32_e32 v2, v4, v2
	v_cmp_ne_u32_e32 vcc, v3, v2
	s_and_saveexec_b64 s[6:7], vcc
	s_xor_b64 s[6:7], exec, s[6:7]
	s_cbranch_execz .LBB0_223
	s_waitcnt lgkmcnt(0)
	v_mov_b32_e32 v0, 0x3100
	global_load_dword v0, v0, s[54:55] offset:1024 sc1
	s_add_u32 s46, s54, 0x3500
	s_addc_u32 s47, s55, 0
	s_waitcnt vmcnt(0)
	v_cmp_eq_u32_e32 vcc, v0, v1
	s_and_saveexec_b64 s[16:17], vcc
	s_cbranch_execz .LBB0_222
	s_add_u32 s44, s52, 0x1200
	s_addc_u32 s45, s53, 0
	s_mov_b32 s62, 1
	s_mov_b64 s[48:49], 0
	v_mov_b32_e32 v0, 0
	s_branch .LBB0_213

.LBB0_329:
	s_or_b64 exec, exec, s[20:21]
	v_cvt_f32_u32_e32 v4, v2
	s_waitcnt vmcnt(0)
	v_readfirstlane_b32 s6, v3
	v_sub_u32_e32 v3, 0, v2
	v_rcp_iflag_f32_e32 v4, v4
	v_add_u32_e32 v5, s6, v1
	v_mul_f32_e32 v4, 0x4f7ffffe, v4
	v_cvt_u32_f32_e32 v4, v4
	v_mul_lo_u32 v1, v3, v4
	v_mul_hi_u32 v1, v4, v1
	v_add_u32_e32 v1, v4, v1
	v_mul_hi_u32 v1, v5, v1
	v_mul_lo_u32 v3, v1, v2
	v_sub_u32_e32 v3, v5, v3
	v_add_u32_e32 v4, 1, v1
	v_cmp_ge_u32_e32 vcc, v3, v2
	s_nop 1
	v_cndmask_b32_e32 v1, v1, v4, vcc
	v_sub_u32_e32 v4, v3, v2
	v_cndmask_b32_e32 v3, v3, v4, vcc
	v_add_u32_e32 v4, 1, v1
	v_cmp_ge_u32_e32 vcc, v3, v2
	v_add_u32_e32 v3, 1, v5
	s_nop 0
	v_cndmask_b32_e32 v1, v1, v4, vcc
	v_mul_lo_u32 v4, v2, v1
	v_add_u32_e32 v2, v4, v2
	v_cmp_ne_u32_e32 vcc, v3, v2
	s_and_saveexec_b64 s[6:7], vcc
	s_xor_b64 s[6:7], exec, s[6:7]
	s_cbranch_execz .LBB0_343
	s_waitcnt lgkmcnt(0)
	v_mov_b32_e32 v0, 0x3100
	global_load_dword v0, v0, s[54:55] offset:1024 sc1
	s_add_u32 s24, s54, 0x3500
	s_addc_u32 s25, s55, 0
	s_waitcnt vmcnt(0)
	v_cmp_eq_u32_e32 vcc, v0, v1
	s_and_saveexec_b64 s[20:21], vcc
	s_cbranch_execz .LBB0_342
	s_add_u32 s22, s52, 0x1200
	s_addc_u32 s23, s53, 0
	s_mov_b32 s46, 1
	s_mov_b64 s[26:27], 0
	v_mov_b32_e32 v0, 0
	s_branch .LBB0_333

.LBB0_423:
	s_or_b64 exec, exec, s[18:19]
	v_cvt_f32_u32_e32 v4, v2
	s_waitcnt vmcnt(0)
	v_readfirstlane_b32 s3, v3
	v_sub_u32_e32 v3, 0, v2
	v_rcp_iflag_f32_e32 v4, v4
	v_add_u32_e32 v5, s3, v1
	v_mul_f32_e32 v4, 0x4f7ffffe, v4
	v_cvt_u32_f32_e32 v4, v4
	v_mul_lo_u32 v1, v3, v4
	v_mul_hi_u32 v1, v4, v1
	v_add_u32_e32 v1, v4, v1
	v_mul_hi_u32 v1, v5, v1
	v_mul_lo_u32 v3, v1, v2
	v_sub_u32_e32 v3, v5, v3
	v_add_u32_e32 v4, 1, v1
	v_cmp_ge_u32_e32 vcc, v3, v2
	s_nop 1
	v_cndmask_b32_e32 v1, v1, v4, vcc
	v_sub_u32_e32 v4, v3, v2
	v_cndmask_b32_e32 v3, v3, v4, vcc
	v_add_u32_e32 v4, 1, v1
	v_cmp_ge_u32_e32 vcc, v3, v2
	v_add_u32_e32 v3, 1, v5
	s_nop 0
	v_cndmask_b32_e32 v1, v1, v4, vcc
	v_mul_lo_u32 v4, v2, v1
	v_add_u32_e32 v2, v4, v2
	v_cmp_ne_u32_e32 vcc, v3, v2
	s_and_saveexec_b64 s[12:13], vcc
	s_xor_b64 s[12:13], exec, s[12:13]
	s_cbranch_execz .LBB0_437
	s_waitcnt lgkmcnt(0)
	v_mov_b32_e32 v0, 0x3100
	global_load_dword v0, v0, s[54:55] offset:1024 sc1
	s_add_u32 s22, s54, 0x3500
	s_addc_u32 s23, s55, 0
	s_waitcnt vmcnt(0)
	v_cmp_eq_u32_e32 vcc, v0, v1
	s_and_saveexec_b64 s[18:19], vcc
	s_cbranch_execz .LBB0_436
	s_add_u32 s20, s52, 0x1200
	s_addc_u32 s21, s53, 0
	s_mov_b32 s3, 1
	s_mov_b64 s[24:25], 0
	v_mov_b32_e32 v0, 0
	s_branch .LBB0_427
